# attention loop K/V prefetch: SGPR-base + 32-bit VGPR-offset global loads (no per-load VALU address math), on top of v037
# baseline (speedup 1.0000x reference)
; DEVFI void finishSM(f32x16& p0, f32x16& p1, float alpha, float& l_reg, bf16x8& pa0, bf16x8& pa1, bf16x8& pa2, bf16x8& pa3) {
; #pragma unroll
;     for (int r = 0; r < 16; ++r) p1[r] = __builtin_amdgcn_exp2f(p1[r]);
;     float ps = 0;
; #pragma unroll
;     for (int r = 0; r < 16; ++r) ps += p0[r];
; #pragma unroll
;     for (int r = 0; r < 16; ++r) ps += p1[r];
;     { auto rr = __builtin_amdgcn_permlane32_swap(__float_as_uint(ps), __float_as_uint(ps), false, false);
;       ps = __uint_as_float(rr[0]) + __uint_as_float(rr[1]); }
;     l_reg = l_reg * alpha + ps;
;     ...
;     PK4(p0, 0, pa0); PK4(p0, 8, pa1); PK4(p1, 0, pa2); PK4(p1, 8, pa3);
.LBB0_1151:
	ds_read_b128 v[0:3], v177 offset:32768
	ds_read_b128 v[4:7], v177 offset:40960
	v_add_f32_e32 v8, v203, v205
	v_add_f32_e32 v8, v189, v8
	s_waitcnt lgkmcnt(1)
	v_mfma_f32_32x32x16_bf16 v[94:109], v[0:3], v[130:133], v[46:61]
	v_add_f32_e32 v8, v204, v8
	v_add_f32_e32 v8, v187, v8
	v_add_f32_e32 v8, v202, v8
	v_add_f32_e32 v8, v186, v8
	v_add_f32_e32 v8, v188, v8
	v_add_f32_e32 v8, v183, v8
	v_add_f32_e32 v8, v185, v8
	s_waitcnt lgkmcnt(0)
	v_mfma_f32_32x32x16_bf16 v[78:93], v[4:7], v[130:133], v[46:61]
	ds_read_b128 v[0:3], v178 offset:32768
	ds_read_b128 v[4:7], v178 offset:40960
	v_add_f32_e32 v8, v163, v8
	v_add_f32_e32 v8, v184, v8
	v_add_f32_e32 v8, v161, v8
	v_add_f32_e32 v8, v182, v8
	v_add_f32_e32 v8, v160, v8
	v_add_f32_e32 v8, v162, v8
	s_waitcnt lgkmcnt(1)
	v_mfma_f32_32x32x16_bf16 v[94:109], v[0:3], v[126:129], v[94:109]
	v_exp_f32_e32 v70, v70
	v_exp_f32_e32 v71, v71
	v_exp_f32_e32 v72, v72
	v_exp_f32_e32 v73, v73
	v_exp_f32_e32 v74, v74
	v_exp_f32_e32 v75, v75
	v_exp_f32_e32 v76, v76
	s_waitcnt lgkmcnt(0)
	v_mfma_f32_32x32x16_bf16 v[78:93], v[4:7], v[126:129], v[78:93]
	ds_read_b128 v[0:3], v176 offset:32768
	ds_read_b128 v[4:7], v176 offset:40960
	v_exp_f32_e32 v77, v77
	s_waitcnt lgkmcnt(1)
	v_mfma_f32_32x32x16_bf16 v[94:109], v[0:3], v[122:125], v[94:109]
	s_waitcnt lgkmcnt(0)
	v_mfma_f32_32x32x16_bf16 v[78:93], v[4:7], v[122:125], v[78:93]
	ds_read_b128 v[0:3], v175 offset:32768
	ds_read_b128 v[4:7], v175 offset:40960
	s_waitcnt lgkmcnt(1)
	v_mfma_f32_32x32x16_bf16 v[94:109], v[0:3], v[118:121], v[94:109]
	s_waitcnt lgkmcnt(0)
	v_mfma_f32_32x32x16_bf16 v[78:93], v[4:7], v[118:121], v[78:93]
	ds_read_b128 v[0:3], v174 offset:32768
	ds_read_b128 v[4:7], v174 offset:40960
	s_waitcnt lgkmcnt(1)
	v_mfma_f32_32x32x16_bf16 v[94:109], v[0:3], v[114:117], v[94:109]
	s_waitcnt lgkmcnt(0)
	v_mfma_f32_32x32x16_bf16 v[78:93], v[4:7], v[114:117], v[78:93]
	ds_read_b128 v[0:3], v172 offset:32768
	ds_read_b128 v[4:7], v172 offset:40960
	s_waitcnt lgkmcnt(1)
	v_mfma_f32_32x32x16_bf16 v[94:109], v[0:3], v[110:113], v[94:109]
	v_exp_f32_e32 v0, v62
	v_exp_f32_e32 v1, v63
	v_exp_f32_e32 v2, v64
	v_exp_f32_e32 v3, v65
	v_add_f32_e32 v8, v0, v8
	v_add_f32_e32 v8, v1, v8
	v_add_f32_e32 v8, v2, v8
	s_waitcnt lgkmcnt(0)
	v_mfma_f32_32x32x16_bf16 v[78:93], v[4:7], v[110:113], v[78:93]
	v_exp_f32_e32 v4, v66
	v_exp_f32_e32 v5, v67
	v_exp_f32_e32 v6, v68
	v_exp_f32_e32 v7, v69
	v_add_f32_e32 v8, v3, v8
	v_add_f32_e32 v8, v4, v8
	v_add_f32_e32 v8, v5, v8
	v_add_f32_e32 v8, v6, v8
	v_add_f32_e32 v8, v7, v8
	v_add_f32_e32 v8, v70, v8
	v_add_f32_e32 v8, v71, v8
	v_add_f32_e32 v8, v72, v8
	v_add_f32_e32 v8, v73, v8
	v_add_f32_e32 v8, v74, v8
	v_add_f32_e32 v8, v75, v8
	v_add_f32_e32 v8, v76, v8
	v_add_f32_e32 v13, v77, v8
	v_mov_b32_e32 v180, v13
	v_cvt_pk_bf16_f32 v8, v203, v205
	v_cvt_pk_bf16_f32 v9, v189, v204
	v_cvt_pk_bf16_f32 v10, v187, v202
	v_cvt_pk_bf16_f32 v11, v186, v188
	v_cvt_pk_bf16_f32 v62, v183, v185
	v_cvt_pk_bf16_f32 v63, v163, v184
	v_cvt_pk_bf16_f32 v64, v161, v182
	v_cvt_pk_bf16_f32 v65, v160, v162
	v_cvt_pk_bf16_f32 v66, v0, v1
	v_cvt_pk_bf16_f32 v67, v2, v3
	v_cvt_pk_bf16_f32 v68, v4, v5
	v_cvt_pk_bf16_f32 v69, v6, v7
	v_cvt_pk_bf16_f32 v70, v70, v71
	v_cvt_pk_bf16_f32 v71, v72, v73
	v_cvt_pk_bf16_f32 v72, v74, v75
	v_cvt_pk_bf16_f32 v73, v76, v77
	s_nop 1
	v_permlane32_swap_b32_e32 v13, v180
	v_permlane32_swap_b32_e32 v8, v10
	v_permlane32_swap_b32_e32 v9, v11
	v_permlane32_swap_b32_e32 v62, v64
	v_permlane32_swap_b32_e32 v63, v65
	v_permlane32_swap_b32_e32 v66, v68
	v_permlane32_swap_b32_e32 v67, v69
	v_permlane32_swap_b32_e32 v70, v72
	v_permlane32_swap_b32_e32 v71, v73
	s_add_u32 s100, s10, 0x2cc48000
	s_addc_u32 s101, s11, 0
	s_nop 0
	global_load_dwordx4 v[0:3], v158, s[100:101]
	s_and_saveexec_b64 s[0:1], s[42:43]
	s_cbranch_execz .LBB0_1153
	global_load_dwordx4 v[138:141], v154, s[100:101]
; #define SBAR() __builtin_amdgcn_sched_barrier(0)
; template <int OFF> DEVFI s16x4 tr_read(int vb) { s16x4 r; asm volatile("ds_read_b64_tr_b16 %0, %1 offset:%2" : "=&v"(r) : "v"(vb), "i"(OFF) : "memory"); return r; }
; template <int NCB, int D0> DEVFI void pv_one(f32x16& od, int vb, bf16x8 pa0, bf16x8 pa1, bf16x8 pa2, bf16x8 pa3) {
;     ...
;     const s16x4 l0 = tr_read<VOFF(0, 0)>(vb), h0 = tr_read<VOFF(0, 1)>(vb), l1 = tr_read<VOFF(1, 0)>(vb), h1 = tr_read<VOFF(1, 1)>(vb);
;     const s16x4 l2 = tr_read<VOFF(2, 0)>(vb), h2 = tr_read<VOFF(2, 1)>(vb), l3 = tr_read<VOFF(3, 0)>(vb), h3 = tr_read<VOFF(3, 1)>(vb);
;     ...
;     asm volatile("s_waitcnt lgkmcnt(0)" ::: "memory"); SBAR();
;     ...
;     od = __builtin_amdgcn_mfma_f32_32x32x16_bf16(pa0, PK(l0, h0), od, 0, 0, 0);
;     od = __builtin_amdgcn_mfma_f32_32x32x16_bf16(pa1, PK(l1, h1), od, 0, 0, 0);
;     od = __builtin_amdgcn_mfma_f32_32x32x16_bf16(pa2, PK(l2, h2), od, 0, 0, 0);
;     od = __builtin_amdgcn_mfma_f32_32x32x16_bf16(pa3, PK(l3, h3), od, 0, 0, 0);
;     ...
; }
.LBB0_1153:
	s_or_b64 exec, exec, s[0:1]
	s_add_u32 s100, s10, 0x2fc30000
	s_addc_u32 s101, s11, 0
	s_nop 0
	global_load_dwordx4 v[4:7], v156, s[100:101]
	ds_read_b64_tr_b16 v[74:75], v171 offset:0
	ds_read_b64_tr_b16 v[76:77], v171 offset:0x400
	ds_read_b64_tr_b16 v[182:183], v171 offset:0x800
	ds_read_b64_tr_b16 v[184:185], v171 offset:0xc00
	ds_read_b64_tr_b16 v[186:187], v171 offset:0x1000
	ds_read_b64_tr_b16 v[188:189], v171 offset:0x1400
	ds_read_b64_tr_b16 v[202:203], v171 offset:0x1800
	ds_read_b64_tr_b16 v[204:205], v171 offset:0x1c00
	s_waitcnt lgkmcnt(6)
	s_nop 0
	v_mfma_f32_32x32x16_bf16 v[30:45], v[8:11], v[74:77], v[30:45]
	ds_read_b64_tr_b16 v[74:75], v171 offset:0x200
	ds_read_b64_tr_b16 v[76:77], v171 offset:0x600
	s_waitcnt lgkmcnt(6)
	v_mfma_f32_32x32x16_bf16 v[30:45], v[62:65], v[182:185], v[30:45]
	ds_read_b64_tr_b16 v[182:183], v171 offset:0xa00
	ds_read_b64_tr_b16 v[184:185], v171 offset:0xe00
	s_waitcnt lgkmcnt(6)
	v_mfma_f32_32x32x16_bf16 v[30:45], v[66:69], v[186:189], v[30:45]
	ds_read_b64_tr_b16 v[186:187], v171 offset:0x1200
	ds_read_b64_tr_b16 v[188:189], v171 offset:0x1600
	s_waitcnt lgkmcnt(6)
	v_mfma_f32_32x32x16_bf16 v[30:45], v[70:73], v[202:205], v[30:45]
	ds_read_b64_tr_b16 v[202:203], v171 offset:0x1a00
	ds_read_b64_tr_b16 v[204:205], v171 offset:0x1e00
	s_waitcnt lgkmcnt(6)
	v_mfma_f32_32x32x16_bf16 v[14:29], v[8:11], v[74:77], v[14:29]
	v_max_f32_e32 v8, v94, v95
	v_max3_f32 v8, v8, v96, v97
	v_max3_f32 v8, v8, v98, v99
	v_max3_f32 v8, v8, v100, v101
	v_max3_f32 v8, v8, v102, v103
	s_waitcnt lgkmcnt(4)
	v_mfma_f32_32x32x16_bf16 v[14:29], v[62:65], v[182:185], v[14:29]
	v_max3_f32 v8, v8, v104, v105
	v_max3_f32 v8, v8, v106, v107
	v_max3_f32 v8, v8, v108, v109
	v_max3_f32 v8, v8, v78, v79
	v_max3_f32 v8, v8, v80, v81
	v_max3_f32 v8, v8, v82, v83
	v_max3_f32 v8, v8, v84, v85
	s_waitcnt lgkmcnt(2)
	v_mfma_f32_32x32x16_bf16 v[14:29], v[66:69], v[186:189], v[14:29]
	v_max3_f32 v8, v8, v86, v87
	v_max3_f32 v8, v8, v88, v89
	v_max3_f32 v8, v8, v90, v91
	v_max3_f32 v8, v8, v92, v93
	v_mov_b32_e32 v9, v8
	s_nop 1
	v_permlane32_swap_b32_e32 v8, v9
	s_waitcnt lgkmcnt(0)
	v_mfma_f32_32x32x16_bf16 v[14:29], v[70:73], v[202:205], v[14:29]
	v_max_f32_e32 v8, v8, v9
	v_cmp_ge_f32_e32 vcc, s33, v8
	s_cmp_eq_u64 vcc, exec
	v_mov_b32_e32 v181, 1.0
	s_cbranch_scc1 .LBB0_1155
	v_max_f32_e32 v8, v8, v8
	v_max_f32_e32 v8, 0, v8
	v_exp_f32_e64 v181, -v8
	v_add_f32_e32 v168, v168, v8
	v_xor_b32_e32 v46, 0x80000000, v168
	v_pk_add_f32 v[94:95], v[94:95], v[8:9] op_sel_hi:[1,0] neg_lo:[0,1] neg_hi:[0,1]
	v_pk_add_f32 v[96:97], v[96:97], v[8:9] op_sel_hi:[1,0] neg_lo:[0,1] neg_hi:[0,1]
	v_pk_add_f32 v[98:99], v[98:99], v[8:9] op_sel_hi:[1,0] neg_lo:[0,1] neg_hi:[0,1]
	v_pk_add_f32 v[100:101], v[100:101], v[8:9] op_sel_hi:[1,0] neg_lo:[0,1] neg_hi:[0,1]
	v_pk_add_f32 v[102:103], v[102:103], v[8:9] op_sel_hi:[1,0] neg_lo:[0,1] neg_hi:[0,1]
	v_pk_add_f32 v[104:105], v[104:105], v[8:9] op_sel_hi:[1,0] neg_lo:[0,1] neg_hi:[0,1]
	v_pk_add_f32 v[106:107], v[106:107], v[8:9] op_sel_hi:[1,0] neg_lo:[0,1] neg_hi:[0,1]
	v_pk_add_f32 v[108:109], v[108:109], v[8:9] op_sel_hi:[1,0] neg_lo:[0,1] neg_hi:[0,1]
	v_sub_f32_e32 v93, v93, v8
	v_sub_f32_e32 v92, v92, v8
	v_sub_f32_e32 v91, v91, v8
	v_sub_f32_e32 v90, v90, v8
	v_sub_f32_e32 v89, v89, v8
	v_sub_f32_e32 v88, v88, v8
	v_sub_f32_e32 v87, v87, v8
	v_sub_f32_e32 v86, v86, v8
	v_sub_f32_e32 v85, v85, v8
	v_sub_f32_e32 v84, v84, v8
	v_sub_f32_e32 v83, v83, v8
	v_sub_f32_e32 v82, v82, v8
	v_sub_f32_e32 v81, v81, v8
	v_sub_f32_e32 v80, v80, v8
	v_sub_f32_e32 v79, v79, v8
	v_sub_f32_e32 v78, v78, v8
	v_mov_b32_e32 v47, v46
	v_mov_b32_e32 v48, v46
	v_mov_b32_e32 v49, v46
	v_mov_b32_e32 v50, v46
	v_mov_b32_e32 v51, v46
	v_mov_b32_e32 v52, v46
	v_mov_b32_e32 v53, v46
	v_mov_b32_e32 v54, v46
	v_mov_b32_e32 v55, v46
	v_mov_b32_e32 v56, v46
	v_mov_b32_e32 v57, v46
	v_mov_b32_e32 v58, v46
	v_mov_b32_e32 v59, v46
	v_mov_b32_e32 v60, v46
	v_mov_b32_e32 v61, v46

; DEVFI void finishSM(f32x16& p0, f32x16& p1, float alpha, float& l_reg, bf16x8& pa0, bf16x8& pa1, bf16x8& pa2, bf16x8& pa3) {
; #pragma unroll
;     for (int r = 0; r < 16; ++r) p1[r] = __builtin_amdgcn_exp2f(p1[r]);
;     float ps = 0;
; #pragma unroll
;     for (int r = 0; r < 16; ++r) ps += p0[r];
; #pragma unroll
;     for (int r = 0; r < 16; ++r) ps += p1[r];
;     { auto rr = __builtin_amdgcn_permlane32_swap(__float_as_uint(ps), __float_as_uint(ps), false, false);
;       ps = __uint_as_float(rr[0]) + __uint_as_float(rr[1]); }
;     l_reg = l_reg * alpha + ps;
;     ...
;     PK4(p0, 0, pa0); PK4(p0, 8, pa1); PK4(p1, 0, pa2); PK4(p1, 8, pa3);
.LBB0_1161:
	v_exp_f32_e32 v8, v94
	v_exp_f32_e32 v9, v96
	v_exp_f32_e32 v10, v98
	v_exp_f32_e32 v11, v100
	v_exp_f32_e32 v205, v95
	v_exp_f32_e32 v204, v97
	v_exp_f32_e32 v203, v99
	v_exp_f32_e32 v202, v101
	v_exp_f32_e32 v187, v102
	v_exp_f32_e32 v189, v103
	v_exp_f32_e32 v185, v104
	v_exp_f32_e32 v188, v105
	v_exp_f32_e32 v183, v106
	v_exp_f32_e32 v186, v107
	v_exp_f32_e32 v182, v108
	v_exp_f32_e32 v184, v109
	s_waitcnt lgkmcnt(0)
	s_barrier
	ds_read_b128 v[62:65], v177 offset:16384
	ds_read_b128 v[206:209], v177 offset:24576
	v_exp_f32_e32 v190, v78
	v_add_f32_e32 v78, v8, v205
	s_waitcnt lgkmcnt(1)
	v_mfma_f32_32x32x16_bf16 v[94:109], v[62:65], v[130:133], v[46:61]
	v_add_f32_e32 v78, v9, v78
	v_add_f32_e32 v78, v204, v78
	v_add_f32_e32 v78, v10, v78
	v_add_f32_e32 v78, v203, v78
	v_add_f32_e32 v78, v11, v78
	v_add_f32_e32 v78, v202, v78
	v_add_f32_e32 v78, v187, v78
	s_waitcnt lgkmcnt(0)
	v_mfma_f32_32x32x16_bf16 v[62:77], v[206:209], v[130:133], v[46:61]
	ds_read_b128 v[206:209], v178 offset:16384
	ds_read_b128 v[210:213], v178 offset:24576
	v_add_f32_e32 v78, v189, v78
	v_add_f32_e32 v78, v185, v78
	v_add_f32_e32 v78, v188, v78
	v_add_f32_e32 v78, v183, v78
	v_exp_f32_e32 v191, v79
	v_add_f32_e32 v78, v186, v78
	s_waitcnt lgkmcnt(1)
	v_mfma_f32_32x32x16_bf16 v[94:109], v[206:209], v[126:129], v[94:109]
	v_add_f32_e32 v78, v182, v78
	v_add_f32_e32 v78, v184, v78
	v_add_f32_e32 v78, v190, v78
	v_add_f32_e32 v78, v191, v78
	v_exp_f32_e32 v85, v85
	v_exp_f32_e32 v86, v86
	v_exp_f32_e32 v87, v87
	s_waitcnt lgkmcnt(0)
	v_mfma_f32_32x32x16_bf16 v[62:77], v[210:213], v[126:129], v[62:77]
	ds_read_b128 v[206:209], v176 offset:16384
	ds_read_b128 v[210:213], v176 offset:24576
	v_exp_f32_e32 v88, v88
	v_exp_f32_e32 v89, v89
	v_exp_f32_e32 v92, v92
	v_exp_f32_e32 v93, v93
	s_waitcnt lgkmcnt(1)
	v_mfma_f32_32x32x16_bf16 v[94:109], v[206:209], v[122:125], v[94:109]
	s_waitcnt lgkmcnt(0)
	v_mfma_f32_32x32x16_bf16 v[62:77], v[210:213], v[122:125], v[62:77]
	ds_read_b128 v[206:209], v175 offset:16384
	ds_read_b128 v[210:213], v175 offset:24576
	s_waitcnt lgkmcnt(1)
	v_mfma_f32_32x32x16_bf16 v[94:109], v[206:209], v[118:121], v[94:109]
	s_waitcnt lgkmcnt(0)
	v_mfma_f32_32x32x16_bf16 v[62:77], v[210:213], v[118:121], v[62:77]
	ds_read_b128 v[206:209], v174 offset:16384
	ds_read_b128 v[210:213], v174 offset:24576
	s_waitcnt lgkmcnt(1)
	v_mfma_f32_32x32x16_bf16 v[94:109], v[206:209], v[114:117], v[94:109]
	s_waitcnt lgkmcnt(0)
	v_mfma_f32_32x32x16_bf16 v[62:77], v[210:213], v[114:117], v[62:77]
	ds_read_b128 v[206:209], v172 offset:16384
	ds_read_b128 v[210:213], v172 offset:24576
	v_cvt_pk_bf16_f32 v8, v8, v205
	v_cvt_pk_bf16_f32 v9, v9, v204
	v_cvt_pk_bf16_f32 v10, v10, v203
	v_cvt_pk_bf16_f32 v11, v11, v202
	s_nop 0
	v_permlane32_swap_b32_e32 v8, v10
	s_waitcnt lgkmcnt(1)
	v_mfma_f32_32x32x16_bf16 v[94:109], v[206:209], v[110:113], v[94:109]
	v_exp_f32_e32 v206, v80
	v_exp_f32_e32 v207, v81
	v_exp_f32_e32 v208, v82
	v_exp_f32_e32 v209, v83
	v_add_f32_e32 v78, v206, v78
	v_add_f32_e32 v78, v207, v78
	v_add_f32_e32 v78, v208, v78
	s_waitcnt lgkmcnt(0)
	v_mfma_f32_32x32x16_bf16 v[62:77], v[210:213], v[110:113], v[62:77]
	v_exp_f32_e32 v210, v84
	v_add_f32_e32 v78, v209, v78
	v_exp_f32_e32 v211, v90
	v_exp_f32_e32 v212, v91
	v_add_f32_e32 v78, v210, v78
	v_add_f32_e32 v78, v85, v78
	v_add_f32_e32 v78, v86, v78
	v_add_f32_e32 v78, v87, v78
	v_add_f32_e32 v78, v88, v78
	v_add_f32_e32 v78, v89, v78
	v_add_f32_e32 v78, v211, v78
	v_add_f32_e32 v78, v212, v78
	v_add_f32_e32 v78, v92, v78
	v_add_f32_e32 v90, v93, v78
	v_mov_b32_e32 v91, v90
	v_cvt_pk_bf16_f32 v78, v187, v189
	v_cvt_pk_bf16_f32 v79, v185, v188
	v_cvt_pk_bf16_f32 v80, v183, v186
	v_cvt_pk_bf16_f32 v81, v182, v184
	v_cvt_pk_bf16_f32 v82, v190, v191
	v_cvt_pk_bf16_f32 v83, v206, v207
	v_cvt_pk_bf16_f32 v84, v208, v209
	v_cvt_pk_bf16_f32 v85, v210, v85
	v_cvt_pk_bf16_f32 v86, v86, v87
	v_cvt_pk_bf16_f32 v87, v88, v89
	v_cvt_pk_bf16_f32 v88, v211, v212
	v_cvt_pk_bf16_f32 v89, v92, v93
	s_nop 1
	v_permlane32_swap_b32_e32 v90, v91
	v_permlane32_swap_b32_e32 v9, v11
	v_permlane32_swap_b32_e32 v78, v80
	v_permlane32_swap_b32_e32 v79, v81
	v_permlane32_swap_b32_e32 v82, v84
	v_permlane32_swap_b32_e32 v83, v85
	v_permlane32_swap_b32_e32 v86, v88
	v_permlane32_swap_b32_e32 v87, v89
	s_cmp_ge_u32 s18, s59
	s_cselect_b64 s[0:1], -1, 0
	s_and_b64 vcc, exec, s[0:1]
	s_cbranch_vccnz .LBB0_1165
	s_add_u32 s100, s10, 0x2cc60000
	s_addc_u32 s101, s11, 0
	s_nop 0
	global_load_dwordx4 v[142:145], v158, s[100:101]
	s_and_saveexec_b64 s[16:17], s[42:43]
	s_cbranch_execz .LBB0_1164
	global_load_dwordx4 v[134:137], v154, s[100:101]
.LBB0_1164:
	s_or_b64 exec, exec, s[16:17]
	s_add_u32 s100, s10, 0x2fc40000
	s_addc_u32 s101, s11, 0
	s_nop 0
	global_load_dwordx4 v[146:149], v156, s[100:101]

; __global__ void __launch_bounds__(512, 2) mega(Args args) {
	.amdhsa_kernel _Z4mega4Args
		.amdhsa_group_segment_fixed_size 0
		.amdhsa_private_segment_fixed_size 0
		.amdhsa_kernarg_size 496
		.amdhsa_user_sgpr_count 2
		.amdhsa_user_sgpr_dispatch_ptr 0
		.amdhsa_user_sgpr_queue_ptr 0
		.amdhsa_user_sgpr_kernarg_segment_ptr 1
		.amdhsa_user_sgpr_dispatch_id 0
		.amdhsa_user_sgpr_kernarg_preload_length 0
		.amdhsa_user_sgpr_kernarg_preload_offset 0
		.amdhsa_user_sgpr_private_segment_size 0
		.amdhsa_uses_dynamic_stack 0
		.amdhsa_enable_private_segment 0
		.amdhsa_system_sgpr_workgroup_id_x 1
		.amdhsa_system_sgpr_workgroup_id_y 0
		.amdhsa_system_sgpr_workgroup_id_z 0
		.amdhsa_system_sgpr_workgroup_info 0
		.amdhsa_system_vgpr_workitem_id 2
		.amdhsa_next_free_vgpr 256
		.amdhsa_next_free_sgpr 102
		.amdhsa_accum_offset 256
		.amdhsa_reserve_vcc 1
		.amdhsa_float_round_mode_32 0
		.amdhsa_float_round_mode_16_64 0
		.amdhsa_float_denorm_mode_32 3
		.amdhsa_float_denorm_mode_16_64 3
		.amdhsa_dx10_clamp 1
		.amdhsa_ieee_mode 1
		.amdhsa_fp16_overflow 0
		.amdhsa_tg_split 0
		.amdhsa_exception_fp_ieee_invalid_op 0
		.amdhsa_exception_fp_denorm_src 0
		.amdhsa_exception_fp_ieee_div_zero 0
		.amdhsa_exception_fp_ieee_overflow 0
		.amdhsa_exception_fp_ieee_underflow 0
		.amdhsa_exception_fp_ieee_inexact 0
		.amdhsa_exception_int_div_zero 0
	.end_amdhsa_kernel

; __global__ void __launch_bounds__(512, 2) mega(Args args) {
amdhsa.kernels:
  - .agpr_count:     0
    .args:
      - .offset:         0
        .size:           240
        .value_kind:     by_value
      - .offset:         240
        .size:           4
        .value_kind:     hidden_block_count_x
      - .offset:         244
        .size:           4
        .value_kind:     hidden_block_count_y
      - .offset:         248
        .size:           4
        .value_kind:     hidden_block_count_z
      - .offset:         252
        .size:           2
        .value_kind:     hidden_group_size_x
      - .offset:         254
        .size:           2
        .value_kind:     hidden_group_size_y
      - .offset:         256
        .size:           2
        .value_kind:     hidden_group_size_z
      - .offset:         258
        .size:           2
        .value_kind:     hidden_remainder_x
      - .offset:         260
        .size:           2
        .value_kind:     hidden_remainder_y
      - .offset:         262
        .size:           2
        .value_kind:     hidden_remainder_z
      - .offset:         280
        .size:           8
        .value_kind:     hidden_global_offset_x
      - .offset:         288
        .size:           8
        .value_kind:     hidden_global_offset_y
      - .offset:         296
        .size:           8
        .value_kind:     hidden_global_offset_z
      - .offset:         304
        .size:           2
        .value_kind:     hidden_grid_dims
      - .offset:         328
        .size:           8
        .value_kind:     hidden_multigrid_sync_arg
      - .offset:         360
        .size:           4
        .value_kind:     hidden_dynamic_lds_size
    .group_segment_fixed_size: 0
    .kernarg_segment_align: 8
    .kernarg_segment_size: 496
    .language:       OpenCL C
    .language_version:
      - 2
      - 0
    .max_flat_workgroup_size: 512
    .name:           _Z4mega4Args
    .private_segment_fixed_size: 0
    .sgpr_count:     108
    .sgpr_spill_count: 162
    .symbol:         _Z4mega4Args.kd
    .uniform_work_group_size: 1
    .uses_dynamic_stack: false
    .vgpr_count:     256
    .vgpr_spill_count: 0
    .wavefront_size: 64
